# indexer sweeps: MFMA score tiles moved to v[18:33]/v[34:49] so pk_fma score and accumulator pairs sit on different VGPR banks
# baseline (speedup 1.0000x reference)
;     ...
;         { f32x16 zero16;
; #pragma unroll
;           for (int r = 0; r < 16; ++r) zero16[r] = 0.f;
;           f32x16 dA0, dA1, dB0, dB1; float wA0, wA1, wB0, wB1;
;           SW_MF(0, dA0, dA1, wA0, wA1);
;           SW_MF(1, dB0, dB1, wB0, wB1); __builtin_amdgcn_sched_barrier(0);
;           SW_VA(dA0, dA1, wA0, wA1);    __builtin_amdgcn_sched_barrier(0);
;           SW_MF(2, dA0, dA1, wA0, wA1); __builtin_amdgcn_sched_barrier(0);
;           SW_VA(dB0, dB1, wB0, wB1);    __builtin_amdgcn_sched_barrier(0);
;           SW_MF(3, dB0, dB1, wB0, wB1); __builtin_amdgcn_sched_barrier(0);
;           SW_VA(dA0, dA1, wA0, wA1);    __builtin_amdgcn_sched_barrier(0);
;           SW_VA(dB0, dB1, wB0, wB1); }
.Lstag_m5:
.Lm5_loop:
	v_mfma_f32_32x32x16_bf16 v[18:33], v[76:79], v[0:3], 0
	v_mfma_f32_32x32x16_bf16 v[18:33], v[72:75], v[4:7], v[18:33]
	ds_read_b128 v[0:3], v165 offset:128
	ds_read_b128 v[4:7], v165 offset:160
	v_mfma_f32_32x32x16_bf16 v[34:49], v[76:79], v[8:11], 0
	v_mfma_f32_32x32x16_bf16 v[34:49], v[72:75], v[12:15], v[34:49]
	ds_read_b128 v[8:11], v165 offset:192
	ds_read_b128 v[12:15], v165 offset:224
	s_add_i32 s1, s2, 1
	s_cmp_lt_u32 s1, s25
	s_cselect_b32 s3, s1, s2
	s_lshl_b32 vcc_lo, s3, 7
	s_and_b32 vcc_lo, vcc_lo, 0x7fffff00
	s_lshl_b32 s3, s3, 5
	s_and_b32 s3, s3, 32
	s_or_b32 s3, vcc_lo, s3
	v_mad_u64_u32 v[114:115], vcc, s3, v223, v[140:141]
	global_load_dwordx4 v[64:67], v[114:115], off
	global_load_dwordx4 v[68:71], v[114:115], off offset:32
	v_pk_mul_f32 v[18:19], v[18:19], v[112:113] clamp
	v_pk_mul_f32 v[20:21], v[20:21], v[112:113] clamp
	v_pk_mul_f32 v[22:23], v[22:23], v[112:113] clamp
	v_pk_mul_f32 v[24:25], v[24:25], v[112:113] clamp
	v_pk_mul_f32 v[26:27], v[26:27], v[112:113] clamp
	v_pk_mul_f32 v[28:29], v[28:29], v[112:113] clamp
	v_pk_mul_f32 v[30:31], v[30:31], v[112:113] clamp
	v_pk_mul_f32 v[32:33], v[32:33], v[112:113] clamp
	v_pk_fma_f32 v[88:89], v[18:19], v[80:81], 0 op_sel_hi:[1,0,0]
	v_pk_fma_f32 v[90:91], v[20:21], v[80:81], 0 op_sel_hi:[1,0,0]
	v_pk_fma_f32 v[92:93], v[22:23], v[80:81], 0 op_sel_hi:[1,0,0]
	v_pk_fma_f32 v[94:95], v[24:25], v[80:81], 0 op_sel_hi:[1,0,0]
	v_pk_fma_f32 v[96:97], v[26:27], v[80:81], 0 op_sel_hi:[1,0,0]
	v_pk_fma_f32 v[98:99], v[28:29], v[80:81], 0 op_sel_hi:[1,0,0]
	v_pk_fma_f32 v[100:101], v[30:31], v[80:81], 0 op_sel_hi:[1,0,0]
	v_pk_fma_f32 v[102:103], v[32:33], v[80:81], 0 op_sel_hi:[1,0,0]
	s_waitcnt lgkmcnt(2)
	v_mfma_f32_32x32x16_bf16 v[18:33], v[76:79], v[0:3], 0
	v_mfma_f32_32x32x16_bf16 v[18:33], v[72:75], v[4:7], v[18:33]
	ds_read_b128 v[0:3], v165 offset:256
	ds_read_b128 v[4:7], v165 offset:288
	v_pk_mul_f32 v[34:35], v[34:35], v[112:113] clamp
	v_pk_mul_f32 v[36:37], v[36:37], v[112:113] clamp
	v_pk_mul_f32 v[38:39], v[38:39], v[112:113] clamp
	v_pk_mul_f32 v[40:41], v[40:41], v[112:113] clamp
	v_pk_mul_f32 v[42:43], v[42:43], v[112:113] clamp
	v_pk_mul_f32 v[44:45], v[44:45], v[112:113] clamp
	v_pk_mul_f32 v[46:47], v[46:47], v[112:113] clamp
	v_pk_mul_f32 v[48:49], v[48:49], v[112:113] clamp
	v_pk_fma_f32 v[88:89], v[34:35], v[104:105], v[88:89] op_sel_hi:[1,0,1]
	v_pk_fma_f32 v[90:91], v[36:37], v[104:105], v[90:91] op_sel_hi:[1,0,1]
	v_pk_fma_f32 v[92:93], v[38:39], v[104:105], v[92:93] op_sel_hi:[1,0,1]
	v_pk_fma_f32 v[94:95], v[40:41], v[104:105], v[94:95] op_sel_hi:[1,0,1]
	v_pk_fma_f32 v[96:97], v[42:43], v[104:105], v[96:97] op_sel_hi:[1,0,1]
	v_pk_fma_f32 v[98:99], v[44:45], v[104:105], v[98:99] op_sel_hi:[1,0,1]
	v_pk_fma_f32 v[100:101], v[46:47], v[104:105], v[100:101] op_sel_hi:[1,0,1]
	v_pk_fma_f32 v[102:103], v[48:49], v[104:105], v[102:103] op_sel_hi:[1,0,1]
	s_waitcnt lgkmcnt(2)
	v_mfma_f32_32x32x16_bf16 v[34:49], v[76:79], v[8:11], 0
	v_mfma_f32_32x32x16_bf16 v[34:49], v[72:75], v[12:15], v[34:49]
	ds_read_b128 v[8:11], v165 offset:320
	ds_read_b128 v[12:15], v165 offset:352
	v_pk_mul_f32 v[18:19], v[18:19], v[112:113] clamp
	v_pk_mul_f32 v[20:21], v[20:21], v[112:113] clamp
	v_pk_mul_f32 v[22:23], v[22:23], v[112:113] clamp
	v_pk_mul_f32 v[24:25], v[24:25], v[112:113] clamp
	v_pk_mul_f32 v[26:27], v[26:27], v[112:113] clamp
	v_pk_mul_f32 v[28:29], v[28:29], v[112:113] clamp
	v_pk_mul_f32 v[30:31], v[30:31], v[112:113] clamp
	v_pk_mul_f32 v[32:33], v[32:33], v[112:113] clamp
	v_pk_fma_f32 v[88:89], v[18:19], v[82:83], v[88:89] op_sel_hi:[1,0,1]
	v_pk_fma_f32 v[90:91], v[20:21], v[82:83], v[90:91] op_sel_hi:[1,0,1]
	v_pk_fma_f32 v[92:93], v[22:23], v[82:83], v[92:93] op_sel_hi:[1,0,1]
	v_pk_fma_f32 v[94:95], v[24:25], v[82:83], v[94:95] op_sel_hi:[1,0,1]
	v_pk_fma_f32 v[96:97], v[26:27], v[82:83], v[96:97] op_sel_hi:[1,0,1]
	v_pk_fma_f32 v[98:99], v[28:29], v[82:83], v[98:99] op_sel_hi:[1,0,1]
	v_pk_fma_f32 v[100:101], v[30:31], v[82:83], v[100:101] op_sel_hi:[1,0,1]
	v_pk_fma_f32 v[102:103], v[32:33], v[82:83], v[102:103] op_sel_hi:[1,0,1]
	s_waitcnt lgkmcnt(2)
	v_mfma_f32_32x32x16_bf16 v[18:33], v[76:79], v[0:3], 0
	v_mfma_f32_32x32x16_bf16 v[18:33], v[72:75], v[4:7], v[18:33]
	ds_read_b128 v[0:3], v165 offset:384
	ds_read_b128 v[4:7], v165 offset:416
	v_pk_mul_f32 v[34:35], v[34:35], v[112:113] clamp
	v_pk_mul_f32 v[36:37], v[36:37], v[112:113] clamp
	v_pk_mul_f32 v[38:39], v[38:39], v[112:113] clamp
	v_pk_mul_f32 v[40:41], v[40:41], v[112:113] clamp
	v_pk_mul_f32 v[42:43], v[42:43], v[112:113] clamp
	v_pk_mul_f32 v[44:45], v[44:45], v[112:113] clamp
	v_pk_mul_f32 v[46:47], v[46:47], v[112:113] clamp
	v_pk_mul_f32 v[48:49], v[48:49], v[112:113] clamp
	v_pk_fma_f32 v[88:89], v[34:35], v[106:107], v[88:89] op_sel_hi:[1,0,1]
	v_pk_fma_f32 v[90:91], v[36:37], v[106:107], v[90:91] op_sel_hi:[1,0,1]
	v_pk_fma_f32 v[92:93], v[38:39], v[106:107], v[92:93] op_sel_hi:[1,0,1]
	v_pk_fma_f32 v[94:95], v[40:41], v[106:107], v[94:95] op_sel_hi:[1,0,1]
	v_pk_fma_f32 v[96:97], v[42:43], v[106:107], v[96:97] op_sel_hi:[1,0,1]
	v_pk_fma_f32 v[98:99], v[44:45], v[106:107], v[98:99] op_sel_hi:[1,0,1]
	v_pk_fma_f32 v[100:101], v[46:47], v[106:107], v[100:101] op_sel_hi:[1,0,1]
	v_pk_fma_f32 v[102:103], v[48:49], v[106:107], v[102:103] op_sel_hi:[1,0,1]
	s_waitcnt lgkmcnt(2)
;     ...
;         { f32x16 zero16;
; #pragma unroll
;           for (int r = 0; r < 16; ++r) zero16[r] = 0.f;
;           f32x16 dA0, dA1, dB0, dB1; float wA0, wA1, wB0, wB1;
;           SW_MF(0, dA0, dA1, wA0, wA1);
;           SW_MF(1, dB0, dB1, wB0, wB1); __builtin_amdgcn_sched_barrier(0);
;           SW_VA(dA0, dA1, wA0, wA1);    __builtin_amdgcn_sched_barrier(0);
;           SW_MF(2, dA0, dA1, wA0, wA1); __builtin_amdgcn_sched_barrier(0);
;           SW_VA(dB0, dB1, wB0, wB1);    __builtin_amdgcn_sched_barrier(0);
;           SW_MF(3, dB0, dB1, wB0, wB1); __builtin_amdgcn_sched_barrier(0);
;           SW_VA(dA0, dA1, wA0, wA1);    __builtin_amdgcn_sched_barrier(0);
;           SW_VA(dB0, dB1, wB0, wB1); }
	v_mfma_f32_32x32x16_bf16 v[34:49], v[76:79], v[8:11], 0
	v_mfma_f32_32x32x16_bf16 v[34:49], v[72:75], v[12:15], v[34:49]
	ds_read_b128 v[8:11], v165 offset:448
	ds_read_b128 v[12:15], v165 offset:480
	v_pk_mul_f32 v[18:19], v[18:19], v[112:113] clamp
	v_pk_mul_f32 v[20:21], v[20:21], v[112:113] clamp
	v_pk_mul_f32 v[22:23], v[22:23], v[112:113] clamp
	v_pk_mul_f32 v[24:25], v[24:25], v[112:113] clamp
	v_pk_mul_f32 v[26:27], v[26:27], v[112:113] clamp
	v_pk_mul_f32 v[28:29], v[28:29], v[112:113] clamp
	v_pk_mul_f32 v[30:31], v[30:31], v[112:113] clamp
	v_pk_mul_f32 v[32:33], v[32:33], v[112:113] clamp
	v_pk_fma_f32 v[88:89], v[18:19], v[84:85], v[88:89] op_sel_hi:[1,0,1]
	v_pk_fma_f32 v[90:91], v[20:21], v[84:85], v[90:91] op_sel_hi:[1,0,1]
	v_pk_fma_f32 v[92:93], v[22:23], v[84:85], v[92:93] op_sel_hi:[1,0,1]
	v_pk_fma_f32 v[94:95], v[24:25], v[84:85], v[94:95] op_sel_hi:[1,0,1]
	v_pk_fma_f32 v[96:97], v[26:27], v[84:85], v[96:97] op_sel_hi:[1,0,1]
	v_pk_fma_f32 v[98:99], v[28:29], v[84:85], v[98:99] op_sel_hi:[1,0,1]
	v_pk_fma_f32 v[100:101], v[30:31], v[84:85], v[100:101] op_sel_hi:[1,0,1]
	v_pk_fma_f32 v[102:103], v[32:33], v[84:85], v[102:103] op_sel_hi:[1,0,1]
	s_waitcnt lgkmcnt(2)
	v_mfma_f32_32x32x16_bf16 v[18:33], v[76:79], v[0:3], 0
	v_mfma_f32_32x32x16_bf16 v[18:33], v[72:75], v[4:7], v[18:33]
	ds_read_b128 v[0:3], v165
	ds_read_b128 v[4:7], v165 offset:32
	v_pk_mul_f32 v[34:35], v[34:35], v[112:113] clamp
	v_pk_mul_f32 v[36:37], v[36:37], v[112:113] clamp
	v_pk_mul_f32 v[38:39], v[38:39], v[112:113] clamp
	v_pk_mul_f32 v[40:41], v[40:41], v[112:113] clamp
	v_pk_mul_f32 v[42:43], v[42:43], v[112:113] clamp
	v_pk_mul_f32 v[44:45], v[44:45], v[112:113] clamp
	v_pk_mul_f32 v[46:47], v[46:47], v[112:113] clamp
	v_pk_mul_f32 v[48:49], v[48:49], v[112:113] clamp
	v_pk_fma_f32 v[88:89], v[34:35], v[108:109], v[88:89] op_sel_hi:[1,0,1]
	v_pk_fma_f32 v[90:91], v[36:37], v[108:109], v[90:91] op_sel_hi:[1,0,1]
	v_pk_fma_f32 v[92:93], v[38:39], v[108:109], v[92:93] op_sel_hi:[1,0,1]
	v_pk_fma_f32 v[94:95], v[40:41], v[108:109], v[94:95] op_sel_hi:[1,0,1]
	v_pk_fma_f32 v[96:97], v[42:43], v[108:109], v[96:97] op_sel_hi:[1,0,1]
	v_pk_fma_f32 v[98:99], v[44:45], v[108:109], v[98:99] op_sel_hi:[1,0,1]
	v_pk_fma_f32 v[100:101], v[46:47], v[108:109], v[100:101] op_sel_hi:[1,0,1]
	v_pk_fma_f32 v[102:103], v[48:49], v[108:109], v[102:103] op_sel_hi:[1,0,1]
	s_waitcnt lgkmcnt(2)
	v_mfma_f32_32x32x16_bf16 v[34:49], v[76:79], v[8:11], 0
	v_mfma_f32_32x32x16_bf16 v[34:49], v[72:75], v[12:15], v[34:49]
	ds_read_b128 v[8:11], v165 offset:64
	ds_read_b128 v[12:15], v165 offset:96
	v_pk_mul_f32 v[18:19], v[18:19], v[112:113] clamp
	v_pk_mul_f32 v[20:21], v[20:21], v[112:113] clamp
	v_pk_mul_f32 v[22:23], v[22:23], v[112:113] clamp
	v_pk_mul_f32 v[24:25], v[24:25], v[112:113] clamp
	v_pk_mul_f32 v[26:27], v[26:27], v[112:113] clamp
	v_pk_mul_f32 v[28:29], v[28:29], v[112:113] clamp
	v_pk_mul_f32 v[30:31], v[30:31], v[112:113] clamp
	v_pk_mul_f32 v[32:33], v[32:33], v[112:113] clamp
	v_pk_fma_f32 v[88:89], v[18:19], v[86:87], v[88:89] op_sel_hi:[1,0,1]
	v_pk_fma_f32 v[90:91], v[20:21], v[86:87], v[90:91] op_sel_hi:[1,0,1]
	v_pk_fma_f32 v[92:93], v[22:23], v[86:87], v[92:93] op_sel_hi:[1,0,1]
	v_pk_fma_f32 v[94:95], v[24:25], v[86:87], v[94:95] op_sel_hi:[1,0,1]
	v_pk_fma_f32 v[96:97], v[26:27], v[86:87], v[96:97] op_sel_hi:[1,0,1]
	v_pk_fma_f32 v[98:99], v[28:29], v[86:87], v[98:99] op_sel_hi:[1,0,1]
	v_pk_fma_f32 v[100:101], v[30:31], v[86:87], v[100:101] op_sel_hi:[1,0,1]
	v_pk_fma_f32 v[102:103], v[32:33], v[86:87], v[102:103] op_sel_hi:[1,0,1]
	v_pk_mul_f32 v[34:35], v[34:35], v[112:113] clamp
	v_pk_mul_f32 v[36:37], v[36:37], v[112:113] clamp
	v_pk_mul_f32 v[38:39], v[38:39], v[112:113] clamp
	v_pk_mul_f32 v[40:41], v[40:41], v[112:113] clamp
	v_pk_mul_f32 v[42:43], v[42:43], v[112:113] clamp
	v_pk_mul_f32 v[44:45], v[44:45], v[112:113] clamp
	v_pk_mul_f32 v[46:47], v[46:47], v[112:113] clamp
	v_pk_mul_f32 v[48:49], v[48:49], v[112:113] clamp
	v_pk_fma_f32 v[88:89], v[34:35], v[110:111], v[88:89] op_sel_hi:[1,0,1]
	v_pk_fma_f32 v[90:91], v[36:37], v[110:111], v[90:91] op_sel_hi:[1,0,1]
	v_pk_fma_f32 v[92:93], v[38:39], v[110:111], v[92:93] op_sel_hi:[1,0,1]
	v_pk_fma_f32 v[94:95], v[40:41], v[110:111], v[94:95] op_sel_hi:[1,0,1]
	v_pk_fma_f32 v[96:97], v[42:43], v[110:111], v[96:97] op_sel_hi:[1,0,1]
	v_pk_fma_f32 v[98:99], v[44:45], v[110:111], v[98:99] op_sel_hi:[1,0,1]
	v_pk_fma_f32 v[100:101], v[46:47], v[110:111], v[100:101] op_sel_hi:[1,0,1]
	v_pk_fma_f32 v[102:103], v[48:49], v[110:111], v[102:103] op_sel_hi:[1,0,1]
	s_waitcnt lgkmcnt(0)
; __device__ __forceinline__ int bucketf(float f) { const unsigned u = __float_as_uint(f); const int idx = (int)((u >> 20) & 0x7FFu); const int c = min(max(idx - 816, 128), 255); return c ^ (((int)u >> 31) & 255); }
;     ...
;         const unsigned s0 = (unsigned)(64 * kt + 32 * kb + 4 * hi);
; #pragma unroll
;         for (int r = 0; r < 16; ++r) { const unsigned s = s0 + (unsigned)((r & 3) + 8 * (r >> 2));
;             if (MODE == 5) { __hip_atomic_fetch_add(hist + 64 * bucketf(sc[r]), 1u, __ATOMIC_RELAXED, __HIP_MEMORY_SCOPE_WORKGROUP); continue; }
;     ...
;         a0 = n0; a1 = n1;
	v_bfe_u32 v48, v88, 20, 11
	v_ashrrev_i32_e32 v49, 31, v88
	v_med3_u32 v48, v48, v117, v118
	v_bitop3_b32 v48, v48, v49, s56 bitop3:0x78
	v_lshl_add_u32 v48, v48, 8, v116
	ds_add_u32 v48, v222
	v_bfe_u32 v50, v89, 20, 11
	v_ashrrev_i32_e32 v51, 31, v89
	v_med3_u32 v50, v50, v117, v118
	v_bitop3_b32 v50, v50, v51, s56 bitop3:0x78
	v_lshl_add_u32 v50, v50, 8, v116
	ds_add_u32 v50, v222
	v_bfe_u32 v52, v90, 20, 11
	v_ashrrev_i32_e32 v53, 31, v90
	v_med3_u32 v52, v52, v117, v118
	v_bitop3_b32 v52, v52, v53, s56 bitop3:0x78
	v_lshl_add_u32 v52, v52, 8, v116
	ds_add_u32 v52, v222
	v_bfe_u32 v54, v91, 20, 11
	v_ashrrev_i32_e32 v55, 31, v91
	v_med3_u32 v54, v54, v117, v118
	v_bitop3_b32 v54, v54, v55, s56 bitop3:0x78
	v_lshl_add_u32 v54, v54, 8, v116
	ds_add_u32 v54, v222
	v_bfe_u32 v48, v92, 20, 11
	v_ashrrev_i32_e32 v49, 31, v92
	v_med3_u32 v48, v48, v117, v118
	v_bitop3_b32 v48, v48, v49, s56 bitop3:0x78
	v_lshl_add_u32 v48, v48, 8, v116
	ds_add_u32 v48, v222
	v_bfe_u32 v50, v93, 20, 11
	v_ashrrev_i32_e32 v51, 31, v93
	v_med3_u32 v50, v50, v117, v118
	v_bitop3_b32 v50, v50, v51, s56 bitop3:0x78
	v_lshl_add_u32 v50, v50, 8, v116
	ds_add_u32 v50, v222
	v_bfe_u32 v52, v94, 20, 11
	v_ashrrev_i32_e32 v53, 31, v94
	v_med3_u32 v52, v52, v117, v118
	v_bitop3_b32 v52, v52, v53, s56 bitop3:0x78
	v_lshl_add_u32 v52, v52, 8, v116
	ds_add_u32 v52, v222
	v_bfe_u32 v54, v95, 20, 11
	v_ashrrev_i32_e32 v55, 31, v95
	v_med3_u32 v54, v54, v117, v118
	v_bitop3_b32 v54, v54, v55, s56 bitop3:0x78
	v_lshl_add_u32 v54, v54, 8, v116
	ds_add_u32 v54, v222
	v_bfe_u32 v48, v96, 20, 11
	v_ashrrev_i32_e32 v49, 31, v96
	v_med3_u32 v48, v48, v117, v118
	v_bitop3_b32 v48, v48, v49, s56 bitop3:0x78
	v_lshl_add_u32 v48, v48, 8, v116
	ds_add_u32 v48, v222
	v_bfe_u32 v50, v97, 20, 11
	v_ashrrev_i32_e32 v51, 31, v97
	v_med3_u32 v50, v50, v117, v118
	v_bitop3_b32 v50, v50, v51, s56 bitop3:0x78
	v_lshl_add_u32 v50, v50, 8, v116
	ds_add_u32 v50, v222
	v_bfe_u32 v52, v98, 20, 11
	v_ashrrev_i32_e32 v53, 31, v98
	v_med3_u32 v52, v52, v117, v118
	v_bitop3_b32 v52, v52, v53, s56 bitop3:0x78
	v_lshl_add_u32 v52, v52, 8, v116
	ds_add_u32 v52, v222
	v_bfe_u32 v54, v99, 20, 11
	v_ashrrev_i32_e32 v55, 31, v99
	v_med3_u32 v54, v54, v117, v118
	v_bitop3_b32 v54, v54, v55, s56 bitop3:0x78
	v_lshl_add_u32 v54, v54, 8, v116
	ds_add_u32 v54, v222
	v_bfe_u32 v48, v100, 20, 11
	v_ashrrev_i32_e32 v49, 31, v100
	v_med3_u32 v48, v48, v117, v118
	v_bitop3_b32 v48, v48, v49, s56 bitop3:0x78
	v_lshl_add_u32 v48, v48, 8, v116
	ds_add_u32 v48, v222
	v_bfe_u32 v50, v101, 20, 11
	v_ashrrev_i32_e32 v51, 31, v101
	v_med3_u32 v50, v50, v117, v118
	v_bitop3_b32 v50, v50, v51, s56 bitop3:0x78
	v_lshl_add_u32 v50, v50, 8, v116
	ds_add_u32 v50, v222
	v_bfe_u32 v52, v102, 20, 11
	v_ashrrev_i32_e32 v53, 31, v102
	v_med3_u32 v52, v52, v117, v118
	v_bitop3_b32 v52, v52, v53, s56 bitop3:0x78
	v_lshl_add_u32 v52, v52, 8, v116
	ds_add_u32 v52, v222
	v_bfe_u32 v54, v103, 20, 11
	v_ashrrev_i32_e32 v55, 31, v103
	v_med3_u32 v54, v54, v117, v118
	v_bitop3_b32 v54, v54, v55, s56 bitop3:0x78
	v_lshl_add_u32 v54, v54, 8, v116
	ds_add_u32 v54, v222
	s_waitcnt vmcnt(0)
	v_mov_b64_e32 v[76:77], v[64:65]
	v_mov_b64_e32 v[78:79], v[66:67]
	v_mov_b64_e32 v[72:73], v[68:69]
	v_mov_b64_e32 v[74:75], v[70:71]
	s_cmp_lg_u32 s25, s1
	s_mov_b32 s2, s1
	s_cbranch_scc1 .Lm5_loop

;     ...
;         const int kt = kt0 + 4 * (it >> 1), kb = it & 1;
;         const int itn = it + 1 < nit ? it + 1 : it;
;         const bf16_t* np = ikp + (size_t)(256 * (itn >> 1) + 32 * (itn & 1)) * NZ; const bf16x8 n0 = *(const bf16x8*)np, n1 = *(const bf16x8*)(np + 16);
;         f32x2v sc2[8];
; #pragma unroll
;         for (int r = 0; r < 8; ++r) sc2[r] = (f32x2v){0.f, 0.f};
;     ...
;         { f32x16 zero16;
; #pragma unroll
;           for (int r = 0; r < 16; ++r) zero16[r] = 0.f;
;           f32x16 dA0, dA1, dB0, dB1; float wA0, wA1, wB0, wB1;
;           SW_MF(0, dA0, dA1, wA0, wA1);
;           SW_MF(1, dB0, dB1, wB0, wB1); __builtin_amdgcn_sched_barrier(0);
;           SW_VA(dA0, dA1, wA0, wA1);    __builtin_amdgcn_sched_barrier(0);
;           SW_MF(2, dA0, dA1, wA0, wA1); __builtin_amdgcn_sched_barrier(0);
;           SW_VA(dB0, dB1, wB0, wB1);    __builtin_amdgcn_sched_barrier(0);
;           SW_MF(3, dB0, dB1, wB0, wB1); __builtin_amdgcn_sched_barrier(0);
;           SW_VA(dA0, dA1, wA0, wA1);    __builtin_amdgcn_sched_barrier(0);
;           SW_VA(dB0, dB1, wB0, wB1); }
.Lstag_m6:
.Lm6_loop:
	v_mfma_f32_32x32x16_bf16 v[18:33], v[132:135], v[0:3], 0
	v_mfma_f32_32x32x16_bf16 v[18:33], v[128:131], v[4:7], v[18:33]
	ds_read_b128 v[0:3], v165 offset:128
	ds_read_b128 v[4:7], v165 offset:160
	v_mfma_f32_32x32x16_bf16 v[34:49], v[132:135], v[8:11], 0
	v_mfma_f32_32x32x16_bf16 v[34:49], v[128:131], v[12:15], v[34:49]
	ds_read_b128 v[8:11], v165 offset:192
	ds_read_b128 v[12:15], v165 offset:224
	s_add_i32 s1, s18, 1
	s_cmp_lt_u32 s1, s25
	s_cselect_b32 s3, s1, s18
	s_lshl_b32 vcc_lo, s3, 7
	s_and_b32 vcc_lo, vcc_lo, 0x7fffff00
	s_lshl_b32 s3, s3, 5
	s_and_b32 s3, s3, 32
	s_or_b32 s3, vcc_lo, s3
	v_mad_u64_u32 v[114:115], vcc, s3, v223, v[140:141]
	s_lshr_b32 s0, s18, 1
	s_lshl_b32 s0, s0, 2
	s_add_i32 s0, s0, s24
	s_lshl_b32 s0, s0, 6
	s_and_b32 s2, s18, 1
	s_lshl_b32 s2, s2, 5
	s_or_b32 s0, s0, s2
	v_or_b32_e32 v124, s0, v159
	global_load_dwordx4 v[64:67], v[114:115], off
	global_load_dwordx4 v[68:71], v[114:115], off offset:32
	v_pk_mul_f32 v[18:19], v[18:19], v[112:113] clamp
	v_pk_mul_f32 v[20:21], v[20:21], v[112:113] clamp
	v_pk_mul_f32 v[22:23], v[22:23], v[112:113] clamp
	v_pk_mul_f32 v[24:25], v[24:25], v[112:113] clamp
	v_pk_mul_f32 v[26:27], v[26:27], v[112:113] clamp
	v_pk_mul_f32 v[28:29], v[28:29], v[112:113] clamp
	v_pk_mul_f32 v[30:31], v[30:31], v[112:113] clamp
	v_pk_mul_f32 v[32:33], v[32:33], v[112:113] clamp
	v_pk_fma_f32 v[88:89], v[18:19], v[80:81], 0 op_sel_hi:[1,0,0]
	v_pk_fma_f32 v[90:91], v[20:21], v[80:81], 0 op_sel_hi:[1,0,0]
	v_pk_fma_f32 v[92:93], v[22:23], v[80:81], 0 op_sel_hi:[1,0,0]
	v_pk_fma_f32 v[94:95], v[24:25], v[80:81], 0 op_sel_hi:[1,0,0]
	v_pk_fma_f32 v[96:97], v[26:27], v[80:81], 0 op_sel_hi:[1,0,0]
	v_pk_fma_f32 v[98:99], v[28:29], v[80:81], 0 op_sel_hi:[1,0,0]
	v_pk_fma_f32 v[100:101], v[30:31], v[80:81], 0 op_sel_hi:[1,0,0]
	v_pk_fma_f32 v[102:103], v[32:33], v[80:81], 0 op_sel_hi:[1,0,0]
	s_waitcnt lgkmcnt(2)
	v_mfma_f32_32x32x16_bf16 v[18:33], v[132:135], v[0:3], 0
	v_mfma_f32_32x32x16_bf16 v[18:33], v[128:131], v[4:7], v[18:33]
	ds_read_b128 v[0:3], v165 offset:256
	ds_read_b128 v[4:7], v165 offset:288
	v_pk_mul_f32 v[34:35], v[34:35], v[112:113] clamp
	v_pk_mul_f32 v[36:37], v[36:37], v[112:113] clamp
	v_pk_mul_f32 v[38:39], v[38:39], v[112:113] clamp
	v_pk_mul_f32 v[40:41], v[40:41], v[112:113] clamp
	v_pk_mul_f32 v[42:43], v[42:43], v[112:113] clamp
	v_pk_mul_f32 v[44:45], v[44:45], v[112:113] clamp
	v_pk_mul_f32 v[46:47], v[46:47], v[112:113] clamp
	v_pk_mul_f32 v[48:49], v[48:49], v[112:113] clamp
	v_pk_fma_f32 v[88:89], v[34:35], v[104:105], v[88:89] op_sel_hi:[1,0,1]
	v_pk_fma_f32 v[90:91], v[36:37], v[104:105], v[90:91] op_sel_hi:[1,0,1]
	v_pk_fma_f32 v[92:93], v[38:39], v[104:105], v[92:93] op_sel_hi:[1,0,1]
	v_pk_fma_f32 v[94:95], v[40:41], v[104:105], v[94:95] op_sel_hi:[1,0,1]
	v_pk_fma_f32 v[96:97], v[42:43], v[104:105], v[96:97] op_sel_hi:[1,0,1]
	v_pk_fma_f32 v[98:99], v[44:45], v[104:105], v[98:99] op_sel_hi:[1,0,1]
	v_pk_fma_f32 v[100:101], v[46:47], v[104:105], v[100:101] op_sel_hi:[1,0,1]
	v_pk_fma_f32 v[102:103], v[48:49], v[104:105], v[102:103] op_sel_hi:[1,0,1]
	s_waitcnt lgkmcnt(2)
	v_mfma_f32_32x32x16_bf16 v[34:49], v[132:135], v[8:11], 0
	v_mfma_f32_32x32x16_bf16 v[34:49], v[128:131], v[12:15], v[34:49]
	ds_read_b128 v[8:11], v165 offset:320
	ds_read_b128 v[12:15], v165 offset:352
	v_pk_mul_f32 v[18:19], v[18:19], v[112:113] clamp
	v_pk_mul_f32 v[20:21], v[20:21], v[112:113] clamp
	v_pk_mul_f32 v[22:23], v[22:23], v[112:113] clamp
	v_pk_mul_f32 v[24:25], v[24:25], v[112:113] clamp
	v_pk_mul_f32 v[26:27], v[26:27], v[112:113] clamp
	v_pk_mul_f32 v[28:29], v[28:29], v[112:113] clamp
	v_pk_mul_f32 v[30:31], v[30:31], v[112:113] clamp
	v_pk_mul_f32 v[32:33], v[32:33], v[112:113] clamp
	v_pk_fma_f32 v[88:89], v[18:19], v[82:83], v[88:89] op_sel_hi:[1,0,1]
	v_pk_fma_f32 v[90:91], v[20:21], v[82:83], v[90:91] op_sel_hi:[1,0,1]
	v_pk_fma_f32 v[92:93], v[22:23], v[82:83], v[92:93] op_sel_hi:[1,0,1]
	v_pk_fma_f32 v[94:95], v[24:25], v[82:83], v[94:95] op_sel_hi:[1,0,1]
	v_pk_fma_f32 v[96:97], v[26:27], v[82:83], v[96:97] op_sel_hi:[1,0,1]
	v_pk_fma_f32 v[98:99], v[28:29], v[82:83], v[98:99] op_sel_hi:[1,0,1]
	v_pk_fma_f32 v[100:101], v[30:31], v[82:83], v[100:101] op_sel_hi:[1,0,1]
	v_pk_fma_f32 v[102:103], v[32:33], v[82:83], v[102:103] op_sel_hi:[1,0,1]
	s_waitcnt lgkmcnt(2)
	v_mfma_f32_32x32x16_bf16 v[18:33], v[132:135], v[0:3], 0
	v_mfma_f32_32x32x16_bf16 v[18:33], v[128:131], v[4:7], v[18:33]
	ds_read_b128 v[0:3], v165 offset:384
	ds_read_b128 v[4:7], v165 offset:416
	v_pk_mul_f32 v[34:35], v[34:35], v[112:113] clamp
	v_pk_mul_f32 v[36:37], v[36:37], v[112:113] clamp
	v_pk_mul_f32 v[38:39], v[38:39], v[112:113] clamp
	v_pk_mul_f32 v[40:41], v[40:41], v[112:113] clamp
	v_pk_mul_f32 v[42:43], v[42:43], v[112:113] clamp
	v_pk_mul_f32 v[44:45], v[44:45], v[112:113] clamp
	v_pk_mul_f32 v[46:47], v[46:47], v[112:113] clamp
	v_pk_mul_f32 v[48:49], v[48:49], v[112:113] clamp
	v_pk_fma_f32 v[88:89], v[34:35], v[106:107], v[88:89] op_sel_hi:[1,0,1]
	v_pk_fma_f32 v[90:91], v[36:37], v[106:107], v[90:91] op_sel_hi:[1,0,1]
	v_pk_fma_f32 v[92:93], v[38:39], v[106:107], v[92:93] op_sel_hi:[1,0,1]
	v_pk_fma_f32 v[94:95], v[40:41], v[106:107], v[94:95] op_sel_hi:[1,0,1]
	v_pk_fma_f32 v[96:97], v[42:43], v[106:107], v[96:97] op_sel_hi:[1,0,1]
	v_pk_fma_f32 v[98:99], v[44:45], v[106:107], v[98:99] op_sel_hi:[1,0,1]
	v_pk_fma_f32 v[100:101], v[46:47], v[106:107], v[100:101] op_sel_hi:[1,0,1]
	v_pk_fma_f32 v[102:103], v[48:49], v[106:107], v[102:103] op_sel_hi:[1,0,1]
	s_waitcnt lgkmcnt(2)
; __device__ __forceinline__ unsigned sortable(float f) { const unsigned u = __float_as_uint(f); return u ^ ((unsigned)((int)u >> 31) | 0x80000000u); }
; __device__ __forceinline__ int bucketf(float f) { const unsigned u = __float_as_uint(f); const int idx = (int)((u >> 20) & 0x7FFu); const int c = min(max(idx - 816, 128), 255); return c ^ (((int)u >> 31) & 255); }
;     ...
;         { f32x16 zero16;
; #pragma unroll
;           for (int r = 0; r < 16; ++r) zero16[r] = 0.f;
;           f32x16 dA0, dA1, dB0, dB1; float wA0, wA1, wB0, wB1;
;           SW_MF(0, dA0, dA1, wA0, wA1);
;           SW_MF(1, dB0, dB1, wB0, wB1); __builtin_amdgcn_sched_barrier(0);
;           SW_VA(dA0, dA1, wA0, wA1);    __builtin_amdgcn_sched_barrier(0);
;           SW_MF(2, dA0, dA1, wA0, wA1); __builtin_amdgcn_sched_barrier(0);
;           SW_VA(dB0, dB1, wB0, wB1);    __builtin_amdgcn_sched_barrier(0);
;           SW_MF(3, dB0, dB1, wB0, wB1); __builtin_amdgcn_sched_barrier(0);
;           SW_VA(dA0, dA1, wA0, wA1);    __builtin_amdgcn_sched_barrier(0);
;           SW_VA(dB0, dB1, wB0, wB1); }
;     ...
;         f32x16 sc;
; #pragma unroll
;         for (int r = 0; r < 16; ++r) sc[r] = sc2[r >> 1][r & 1];
;         const unsigned s0 = (unsigned)(64 * kt + 32 * kb + 4 * hi);
; #pragma unroll
;         for (int r = 0; r < 16; ++r) { const unsigned s = s0 + (unsigned)((r & 3) + 8 * (r >> 2));
;             if (MODE == 5) { __hip_atomic_fetch_add(hist + 64 * bucketf(sc[r]), 1u, __ATOMIC_RELAXED, __HIP_MEMORY_SCOPE_WORKGROUP); continue; }
;             if (MODE == 6) {
;                 if (sc[r] >= t_hi) { const unsigned pos = __hip_atomic_fetch_add(cnt, 1u, __ATOMIC_RELAXED, __HIP_MEMORY_SCOPE_WORKGROUP); sel[pos & 255u] = (unsigned short)s; }
;                 else if (sc[r] >= t_lo) { const unsigned key = (sortable(sc[r]) & 0xFFFFE000u) | (8191u - s);
;                     const unsigned pos = __hip_atomic_fetch_add(ccnt, 1u, __ATOMIC_RELAXED, __HIP_MEMORY_SCOPE_WORKGROUP); cand[pos & (DS_CAP - 1)] = key; }
	v_mfma_f32_32x32x16_bf16 v[34:49], v[132:135], v[8:11], 0
	v_mfma_f32_32x32x16_bf16 v[34:49], v[128:131], v[12:15], v[34:49]
	ds_read_b128 v[8:11], v165 offset:448
	ds_read_b128 v[12:15], v165 offset:480
	v_pk_mul_f32 v[18:19], v[18:19], v[112:113] clamp
	v_pk_mul_f32 v[20:21], v[20:21], v[112:113] clamp
	v_pk_mul_f32 v[22:23], v[22:23], v[112:113] clamp
	v_pk_mul_f32 v[24:25], v[24:25], v[112:113] clamp
	v_pk_mul_f32 v[26:27], v[26:27], v[112:113] clamp
	v_pk_mul_f32 v[28:29], v[28:29], v[112:113] clamp
	v_pk_mul_f32 v[30:31], v[30:31], v[112:113] clamp
	v_pk_mul_f32 v[32:33], v[32:33], v[112:113] clamp
	v_pk_fma_f32 v[88:89], v[18:19], v[84:85], v[88:89] op_sel_hi:[1,0,1]
	v_pk_fma_f32 v[90:91], v[20:21], v[84:85], v[90:91] op_sel_hi:[1,0,1]
	v_pk_fma_f32 v[92:93], v[22:23], v[84:85], v[92:93] op_sel_hi:[1,0,1]
	v_pk_fma_f32 v[94:95], v[24:25], v[84:85], v[94:95] op_sel_hi:[1,0,1]
	v_pk_fma_f32 v[96:97], v[26:27], v[84:85], v[96:97] op_sel_hi:[1,0,1]
	v_pk_fma_f32 v[98:99], v[28:29], v[84:85], v[98:99] op_sel_hi:[1,0,1]
	v_pk_fma_f32 v[100:101], v[30:31], v[84:85], v[100:101] op_sel_hi:[1,0,1]
	v_pk_fma_f32 v[102:103], v[32:33], v[84:85], v[102:103] op_sel_hi:[1,0,1]
	s_waitcnt lgkmcnt(2)
	v_mfma_f32_32x32x16_bf16 v[18:33], v[132:135], v[0:3], 0
	v_mfma_f32_32x32x16_bf16 v[18:33], v[128:131], v[4:7], v[18:33]
	ds_read_b128 v[0:3], v165
	ds_read_b128 v[4:7], v165 offset:32
	v_pk_mul_f32 v[34:35], v[34:35], v[112:113] clamp
	v_pk_mul_f32 v[36:37], v[36:37], v[112:113] clamp
	v_pk_mul_f32 v[38:39], v[38:39], v[112:113] clamp
	v_pk_mul_f32 v[40:41], v[40:41], v[112:113] clamp
	v_pk_mul_f32 v[42:43], v[42:43], v[112:113] clamp
	v_pk_mul_f32 v[44:45], v[44:45], v[112:113] clamp
	v_pk_mul_f32 v[46:47], v[46:47], v[112:113] clamp
	v_pk_mul_f32 v[48:49], v[48:49], v[112:113] clamp
	v_pk_fma_f32 v[88:89], v[34:35], v[108:109], v[88:89] op_sel_hi:[1,0,1]
	v_pk_fma_f32 v[90:91], v[36:37], v[108:109], v[90:91] op_sel_hi:[1,0,1]
	v_pk_fma_f32 v[92:93], v[38:39], v[108:109], v[92:93] op_sel_hi:[1,0,1]
	v_pk_fma_f32 v[94:95], v[40:41], v[108:109], v[94:95] op_sel_hi:[1,0,1]
	v_pk_fma_f32 v[96:97], v[42:43], v[108:109], v[96:97] op_sel_hi:[1,0,1]
	v_pk_fma_f32 v[98:99], v[44:45], v[108:109], v[98:99] op_sel_hi:[1,0,1]
	v_pk_fma_f32 v[100:101], v[46:47], v[108:109], v[100:101] op_sel_hi:[1,0,1]
	v_pk_fma_f32 v[102:103], v[48:49], v[108:109], v[102:103] op_sel_hi:[1,0,1]
	s_waitcnt lgkmcnt(2)
	v_mfma_f32_32x32x16_bf16 v[34:49], v[132:135], v[8:11], 0
	v_mfma_f32_32x32x16_bf16 v[34:49], v[128:131], v[12:15], v[34:49]
	ds_read_b128 v[8:11], v165 offset:64
	ds_read_b128 v[12:15], v165 offset:96
	v_pk_mul_f32 v[18:19], v[18:19], v[112:113] clamp
	v_pk_mul_f32 v[20:21], v[20:21], v[112:113] clamp
	v_pk_mul_f32 v[22:23], v[22:23], v[112:113] clamp
	v_pk_mul_f32 v[24:25], v[24:25], v[112:113] clamp
	v_pk_mul_f32 v[26:27], v[26:27], v[112:113] clamp
	v_pk_mul_f32 v[28:29], v[28:29], v[112:113] clamp
	v_pk_mul_f32 v[30:31], v[30:31], v[112:113] clamp
	v_pk_mul_f32 v[32:33], v[32:33], v[112:113] clamp
	v_pk_fma_f32 v[88:89], v[18:19], v[86:87], v[88:89] op_sel_hi:[1,0,1]
	v_pk_fma_f32 v[90:91], v[20:21], v[86:87], v[90:91] op_sel_hi:[1,0,1]
	v_pk_fma_f32 v[92:93], v[22:23], v[86:87], v[92:93] op_sel_hi:[1,0,1]
	v_pk_fma_f32 v[94:95], v[24:25], v[86:87], v[94:95] op_sel_hi:[1,0,1]
	v_pk_fma_f32 v[96:97], v[26:27], v[86:87], v[96:97] op_sel_hi:[1,0,1]
	v_pk_fma_f32 v[98:99], v[28:29], v[86:87], v[98:99] op_sel_hi:[1,0,1]
	v_pk_fma_f32 v[100:101], v[30:31], v[86:87], v[100:101] op_sel_hi:[1,0,1]
	v_pk_fma_f32 v[102:103], v[32:33], v[86:87], v[102:103] op_sel_hi:[1,0,1]
	v_pk_mul_f32 v[34:35], v[34:35], v[112:113] clamp
	v_pk_mul_f32 v[36:37], v[36:37], v[112:113] clamp
	v_pk_mul_f32 v[38:39], v[38:39], v[112:113] clamp
	v_pk_mul_f32 v[40:41], v[40:41], v[112:113] clamp
	v_pk_mul_f32 v[42:43], v[42:43], v[112:113] clamp
	v_pk_mul_f32 v[44:45], v[44:45], v[112:113] clamp
	v_pk_mul_f32 v[46:47], v[46:47], v[112:113] clamp
	v_pk_mul_f32 v[48:49], v[48:49], v[112:113] clamp
	v_pk_fma_f32 v[88:89], v[34:35], v[110:111], v[88:89] op_sel_hi:[1,0,1]
	v_pk_fma_f32 v[90:91], v[36:37], v[110:111], v[90:91] op_sel_hi:[1,0,1]
	v_pk_fma_f32 v[92:93], v[38:39], v[110:111], v[92:93] op_sel_hi:[1,0,1]
	v_pk_fma_f32 v[94:95], v[40:41], v[110:111], v[94:95] op_sel_hi:[1,0,1]
	v_pk_fma_f32 v[96:97], v[42:43], v[110:111], v[96:97] op_sel_hi:[1,0,1]
	v_pk_fma_f32 v[98:99], v[44:45], v[110:111], v[98:99] op_sel_hi:[1,0,1]
	v_pk_fma_f32 v[100:101], v[46:47], v[110:111], v[100:101] op_sel_hi:[1,0,1]
	v_pk_fma_f32 v[102:103], v[48:49], v[110:111], v[102:103] op_sel_hi:[1,0,1]
	s_waitcnt lgkmcnt(0)
	v_cmp_ge_f32_e64 s[40:41], v88, v122
	v_cmp_ge_f32_e64 s[42:43], v88, v123
	v_mov_b32_e32 v18, v124
	s_andn2_b64 s[42:43], s[42:43], s[40:41]
	s_mov_b64 exec, s[40:41]
	ds_add_rtn_u32 v16, v180, v222
	s_mov_b64 exec, s[42:43]
	ds_add_rtn_u32 v16, v171, v222
	s_mov_b64 exec, -1
	v_cmp_ge_f32_e64 s[44:45], v89, v122
	v_cmp_ge_f32_e64 s[22:23], v89, v123
	v_or_b32_e32 v19, 1, v124
	s_andn2_b64 s[22:23], s[22:23], s[44:45]
	s_mov_b64 exec, s[44:45]
	ds_add_rtn_u32 v17, v180, v222
	s_mov_b64 exec, s[22:23]
	ds_add_rtn_u32 v17, v171, v222
	s_mov_b64 exec, -1
	v_cmp_ge_f32_e64 s[20:21], v90, v122
	v_cmp_ge_f32_e64 s[2:3], v90, v123
	v_or_b32_e32 v24, 2, v124
	s_andn2_b64 s[2:3], s[2:3], s[20:21]
	s_mov_b64 exec, s[20:21]
	ds_add_rtn_u32 v23, v180, v222
	s_mov_b64 exec, s[2:3]
	ds_add_rtn_u32 v23, v171, v222
	s_mov_b64 exec, -1
	s_waitcnt lgkmcnt(4)
	v_and_b32_e32 v16, 0xff, v16
	s_mov_b64 exec, s[40:41]
	v_lshl_add_u32 v20, v16, 1, v179
	ds_write_b16 v20, v18
	s_mov_b64 exec, s[42:43]
	s_cbranch_execz .Lm6_nb0
	v_ashrrev_i32_e32 v22, 31, v88
	v_sub_u32_e32 v18, 0x1fff, v18
	v_lshl_add_u32 v20, v16, 2, v169
	v_bitop3_b32 v21, v22, v88, s64 bitop3:0x36
	v_and_or_b32 v21, v21, s65, v18
	ds_write_b32 v20, v21
